# P8 final norm of prompt rows overlapped with the third down-proj GEMM round (counter hand-off), XCD chunk 64 tile map
# baseline (speedup 1.0000x reference)
.LBB0_1069:
	s_or_b64 exec, exec, s[0:1]
	v_mov_b32_e32 v16, v176
	s_waitcnt lgkmcnt(0)
	s_barrier
	v_readlane_b32 s101, v239, 2
	s_nop 0
	s_cmp_eq_u32 s101, 0x100
	s_cselect_b32 s100, 0x2000, 0
	s_cmpk_lt_i32 s2, 0x240
	v_readfirstlane_b32 s18, v16
	s_cbranch_scc0 .LBB0_1089
	v_lshlrev_b32_e32 v0, 4, v16
	v_add_u32_e32 v1, 0x2000, v0
	v_ashrrev_i32_e32 v2, 31, v1
	v_lshrrev_b32_e32 v2, 22, v2
	v_add_u32_e32 v2, v1, v2
	v_ashrrev_i32_e32 v8, 10, v2
	v_mul_i32_i24_e32 v2, 0x400, v8
	v_sub_u32_e32 v1, v1, v2
	v_lshrrev_b32_e32 v2, 4, v1
	v_bitop3_b32 v1, v2, v1, 32 bitop3:0x6c
	v_ashrrev_i32_e32 v2, 31, v1
	v_lshrrev_b32_e32 v2, 26, v2
	v_add_u32_e32 v2, v1, v2
	v_lshlrev_b32_e32 v3, 3, v8
	v_ashrrev_i32_e32 v9, 6, v2
	v_and_b32_e32 v3, -16, v3
	v_add_u32_e32 v3, v9, v3
	v_and_b32_e32 v4, 3, v9
	s_mov_b32 s5, 0x7fffe0
	v_lshrrev_b32_e32 v5, 2, v3
	v_lshlrev_b32_e32 v6, 1, v3
	v_and_b32_e32 v2, 0xc0, v2
	v_and_or_b32 v4, v3, s5, v4
	v_and_b32_e32 v5, 4, v5
	v_and_b32_e32 v6, 24, v6
	v_sub_u32_e32 v1, v1, v2
	v_mov_b32_e32 v2, 1
	v_or3_b32 v4, v4, v5, v6
	v_lshlrev_b32_e32 v5, 5, v8
	v_ashrrev_i16_sdwa v1, v2, sext(v1) dst_sel:DWORD dst_unused:UNUSED_PAD src0_sel:DWORD src1_sel:BYTE_0
	s_movk_i32 s4, 0x1600
	v_and_b32_e32 v10, 32, v5
	v_bfe_i32 v11, v1, 0, 16
	v_mul_u32_u24_e32 v4, 0x1600, v4
	v_add_u32_e32 v1, v10, v11
	v_mul_lo_u32 v3, v3, s4
	v_add_lshl_u32 v128, v4, v1, 1
	v_add_lshl_u32 v130, v1, v3, 1
	v_bfe_i32 v1, v16, 27, 1
	v_lshrrev_b32_e32 v1, 22, v1
	v_add_u32_e32 v1, v0, v1
	v_and_b32_e32 v1, 0xfffffc00, v1
	v_sub_u32_e32 v0, v0, v1
	v_lshrrev_b32_e32 v1, 4, v0
	v_bitop3_b32 v1, v1, v0, 32 bitop3:0x6c
	v_ashrrev_i32_e32 v0, 31, v0
	v_lshrrev_b32_e32 v0, 26, v0
	v_add_u32_e32 v0, v1, v0
	v_ashrrev_i32_e32 v12, 6, v0
	v_ashrrev_i32_e32 v0, 31, v16
	v_lshrrev_b32_e32 v0, 26, v0
	v_add_u32_e32 v0, v16, v0
	v_ashrrev_i32_e32 v13, 6, v0
	v_lshlrev_b32_e32 v0, 3, v13
	v_and_b32_e32 v0, -16, v0
	v_add_u32_e32 v0, v12, v0
	v_and_b32_e32 v3, 3, v12
	v_and_or_b32 v3, v0, s5, v3
	s_lshr_b32 s5, s3, 29
	s_add_i32 s5, s2, s5
	s_ashr_i32 s1, s18, 6
	s_ashr_i32 s6, s5, 3
	s_and_b32 s5, s5, -8
	s_ashr_i32 s0, s18, 8
	s_lshl_b32 s19, s1, 10
	s_sub_i32 s5, s2, s5
	s_cmp_lt_i32 s5, 0
	s_movk_i32 s20, 0x49
	s_cselect_b32 s7, s20, 0x48
	s_cmp_lg_u32 s100, 0
	s_cselect_b32 s7, 64, s7
	s_mul_i32 s5, s5, s7
	s_add_i32 s5, s5, s6
	s_ashr_i32 s6, s5, 31
	s_lshr_b32 s6, s6, 26
	s_add_i32 s6, s5, s6
	s_ashr_i32 s7, s6, 6
	s_and_b32 s6, s6, 0xffc0
	s_sub_i32 s5, s5, s6
	s_bfe_i32 s6, s5, 0x80000
	s_lshr_b32 s6, s6, 7
	s_bfe_u32 s8, s6, 0x20006
	s_add_i32 s8, s5, s8
	s_and_b32 s10, s8, 0xfc
	s_bfe_i32 s9, s8, 0x80000
	s_sub_i32 s10, s5, s10
	s_lshl_b32 s7, s7, 2
	s_sext_i32_i16 s9, s9
	s_sext_i32_i8 s10, s10
	s_ashr_i32 s9, s9, 2
	s_add_i32 s42, s7, s10
	s_bfe_u32 s7, s8, 0x10007
	s_bfe_u32 s6, s6, 0x30005
	s_add_i32 s7, s9, s7
	s_add_i32 s5, s5, s6
	s_and_b32 s7, s7, 0xfffe
	s_bfe_i32 s5, s5, 0x80000
	v_lshrrev_b32_e32 v4, 2, v0
	v_lshlrev_b32_e32 v5, 1, v0
	s_sub_i32 s7, s9, s7
	s_sext_i32_i16 s5, s5
	v_and_b32_e32 v4, 4, v4
	v_and_b32_e32 v5, 24, v5
	s_sext_i32_i16 s43, s7
	s_ashr_i32 s44, s5, 3
	v_or3_b32 v3, v3, v4, v5
	v_lshlrev_b32_e32 v4, 5, v13
	s_mul_i32 s7, s43, 0x1600
	s_mul_i32 s9, s44, 0x2c0000
	v_and_b32_e32 v14, 32, v4
	v_mul_i32_i24_e32 v4, 64, v12
	s_ashr_i32 s8, s7, 31
	s_ashr_i32 s10, s9, 31
	v_readlane_b32 s12, v238, 23
	v_sub_u32_e32 v1, v1, v4
	v_readlane_b32 s13, v238, 24
	s_add_u32 s9, s12, s9
	v_ashrrev_i16_sdwa v1, v2, sext(v1) dst_sel:DWORD dst_unused:UNUSED_PAD src0_sel:DWORD src1_sel:BYTE_0
	s_addc_u32 s10, s13, s10
	v_bfe_i32 v15, v1, 0, 16
	s_add_u32 s12, s9, s7
	v_mul_u32_u24_e32 v3, 0x1600, v3
	v_add_u32_e32 v1, v14, v15
	s_addc_u32 s13, s10, s8
	s_add_i32 s21, s19, 0
	v_add_lshl_u32 v132, v3, v1, 1
	s_add_i32 m0, s21, 0x10000
	s_mul_i32 s6, s42, 0x2c0000
	global_load_lds_dwordx4 v132, s[12:13]
	s_add_i32 m0, s21, 0x12000
	v_readlane_b32 s9, v239, 9
	s_mul_hi_i32 s5, s42, 0x2c0000
	s_add_u32 s6, s9, s6
	v_readlane_b32 s9, v239, 10
	s_addc_u32 s5, s9, s5
	v_mul_lo_u32 v0, v0, s4
	s_add_u32 s10, s6, s7
	v_add_lshl_u32 v134, v1, v0, 1
	global_load_lds_dwordx4 v128, s[12:13]
	s_addc_u32 s11, s5, s8
	s_mov_b32 m0, s21
	s_add_i32 s22, s21, 0x2000
	global_load_lds_dwordx4 v134, s[10:11]
	s_mov_b32 m0, s22
	s_add_u32 s6, s12, 0x160000
	global_load_lds_dwordx4 v130, s[10:11]
	s_addc_u32 s7, s13, 0
	s_add_i32 m0, s21, 0x14000
	v_mov_b32_e32 v133, 0
	global_load_lds_dwordx4 v132, s[6:7]
	s_add_i32 m0, s21, 0x16000
	v_mov_b32_e32 v129, v133
	global_load_lds_dwordx4 v128, s[6:7]
	s_add_u32 s6, s10, 0x160000
	s_addc_u32 s7, s11, 0
	s_add_i32 s23, s21, 0x4000
	s_mov_b32 m0, s23
	s_add_i32 s24, s21, 0x6000
	global_load_lds_dwordx4 v134, s[6:7]
	s_mov_b32 m0, s24
	v_mov_b32_e32 v135, v133
	global_load_lds_dwordx4 v130, s[6:7]
	v_mov_b32_e32 v131, v133
	s_movk_i32 s25, 0x2000
	s_mov_b32 s26, 0
	v_lshl_add_u64 v[6:7], s[12:13], 0, v[132:133]
	v_lshl_add_u64 v[4:5], s[12:13], 0, v[128:129]
	v_lshl_add_u64 v[2:3], s[10:11], 0, v[134:135]
	v_lshl_add_u64 v[0:1], s[10:11], 0, v[130:131]
	s_cmp_lg_u32 s0, 1
	s_mov_b32 s5, 0x16000
	s_cbranch_scc1 .LBB0_1072
	s_barrier

.LBB0_1073:
	s_and_b64 vcc, exec, s[4:5]
	s_mov_b32 s43, s39
	s_mov_b32 s44, s41
	s_mov_b32 s42, s40
	s_mov_b64 s[12:13], s[8:9]
	s_mov_b64 s[10:11], s[6:7]
	global_store_dwordx4 v[154:155], v[4:7], off offset:512
	global_store_dwordx4 v[154:155], v[0:3], off offset:528
	s_cmp_eq_u32 s100, 0
	s_cbranch_scc1 .Lp7sig_skip
	s_cmp_lg_u32 s26, 2
	s_cbranch_scc1 .Lp7sig_skip
	s_cmp_lg_u64 s[4:5], 0
	s_cbranch_scc1 .Lp7sig_skip
	s_waitcnt vmcnt(0)
	s_barrier
	s_barrier
	s_mov_b64 s[98:99], exec
	v_readlane_b32 s101, v239, 4
	s_nop 0
	s_and_b32 exec_lo, exec_lo, s101
	s_mov_b32 exec_hi, 0
	s_cbranch_execz .Lp7sig_done
	buffer_wbl2 sc1
	s_waitcnt vmcnt(0)
	v_mov_b32_e32 v240, 0x17feb000
	v_mov_b32_e32 v241, 1
	global_atomic_add v240, v241, s[30:31] offset:128
.Lp7sig_done:
	s_mov_b64 exec, s[98:99]
.Lp7sig_skip:
	s_cbranch_vccnz .LBB0_1086
.LBB0_1074:
	s_add_i32 s26, s26, 1
	v_readlane_b32 s6, v239, 2
	s_mul_i32 s4, s26, s55
	s_mul_hi_u32 s5, s26, s6
	s_add_i32 s5, s5, s4
	s_mul_i32 s4, s26, s6
	s_add_u32 s8, s4, s2
	s_addc_u32 s9, s5, s3
	s_mov_b32 s101, s8
	v_readlane_b32 s7, v239, 3
	v_cmp_gt_i64_e64 s[4:5], s[8:9], v[142:143]
	v_cmp_lt_i64_e64 s[6:7], s[8:9], v[140:141]
	s_and_b64 vcc, exec, s[4:5]
	s_cbranch_vccnz .LBB0_1076
	s_ashr_i32 s9, s8, 31
	s_lshr_b32 s9, s9, 29
	s_add_i32 s9, s8, s9
	s_ashr_i32 s14, s9, 3
	s_and_b32 s9, s9, -8
	s_sub_i32 s8, s8, s9
	s_cmp_lt_i32 s8, 0
	s_cselect_b32 s9, s20, 0x48
	s_cmp_lg_u32 s100, 0
	s_cselect_b32 s9, 64, s9
	s_mul_i32 s8, s8, s9
	s_add_i32 s8, s8, s14
	s_movk_i32 s98, 0x200
	s_cmp_lg_u32 s100, 0
	s_cselect_b32 s98, s98, 0x7fffffff
	s_cmp_ge_i32 s101, s98
	s_cselect_b32 s8, s101, s8
	s_ashr_i32 s9, s8, 31
	s_lshr_b32 s9, s9, 26
	s_add_i32 s9, s8, s9
	s_ashr_i32 s14, s9, 6
	s_lshl_b32 s14, s14, 2
	s_sub_i32 s15, 36, s14
	s_min_i32 s15, s15, 4
	s_abs_i32 s16, s15
	v_cvt_f32_u32_e32 v0, s16
	s_sub_i32 s34, 0, s16
	s_andn2_b32 s9, s9, 63
	s_sub_i32 s8, s8, s9
	v_rcp_iflag_f32_e32 v0, v0
	s_abs_i32 s9, s8
	s_xor_b32 s17, s8, s15
	s_ashr_i32 s17, s17, 31
	v_mul_f32_e32 v0, 0x4f7ffffe, v0
	v_cvt_u32_f32_e32 v0, v0
	s_mov_b32 s39, 0
	v_readfirstlane_b32 s40, v0
	s_mul_i32 s34, s34, s40
	s_mul_hi_u32 s34, s40, s34
	s_add_i32 s40, s40, s34
	s_mul_hi_u32 s34, s9, s40
	s_mul_i32 s40, s34, s16
	s_sub_i32 s9, s9, s40
	s_add_i32 s41, s34, 1
	s_sub_i32 s40, s9, s16
	s_cmp_ge_u32 s9, s16
	s_cselect_b32 s34, s41, s34
	s_cselect_b32 s9, s40, s9
	s_add_i32 s40, s34, 1
	s_cmp_ge_u32 s9, s16
	s_cselect_b32 s9, s40, s34
	s_xor_b32 s9, s9, s17
	s_sub_i32 s41, s9, s17
	s_mul_i32 s9, s41, s15
	s_sub_i32 s8, s8, s9
	s_add_i32 s40, s14, s8

.LBB0_1088:
	v_readlane_b32 s19, v239, 6
	s_barrier
	s_cmp_eq_u32 s100, 0
	s_cbranch_scc1 .Lp8e_skip
	s_cmp_lg_u32 s26, 2
	s_cbranch_scc1 .Lp8e_skip
	s_mov_b64 s[98:99], exec
	v_readlane_b32 s101, v239, 4
	s_nop 0
	s_and_b32 exec_lo, exec_lo, s101
	s_mov_b32 exec_hi, 0
	s_cbranch_execz .Lp8e_sig_done
	buffer_wbl2 sc1
	s_waitcnt vmcnt(0)
	v_mov_b32_e32 v240, 0x17feb000
	v_mov_b32_e32 v241, 1
	global_atomic_add v240, v241, s[30:31] offset:128
	s_mov_b32 s101, 0
.Lp8e_poll:
	global_load_dword v241, v240, s[30:31] offset:128 sc1
	s_add_i32 s101, s101, 1
	s_waitcnt vmcnt(0)
	v_cmp_gt_u32_e32 vcc, 0x180, v241
	s_cbranch_vccz .Lp8e_ready
	s_cmpk_gt_u32 s101, 0x1000
	s_cbranch_scc1 .Lp8e_ready
	s_sleep 2
	s_branch .Lp8e_poll

.Lp8e_sig_done:
	s_mov_b64 exec, s[98:99]
	s_barrier
	s_movk_i32 s0, 0x2000
	s_add_i32 s101, s2, 0xffffffc0
	v_ashrrev_i32_e32 v0, 6, v176
	v_lshl_add_u32 v0, s101, 3, v0
	v_cmp_gt_i32_e32 vcc, s0, v0
	s_and_saveexec_b64 s[0:1], vcc
	s_cbranch_execz .Lp8e_end
	v_lshlrev_b32_e32 v1, 2, v176
	v_and_b32_e32 v14, 0xfc, v1
	v_mbcnt_lo_u32_b32 v1, -1, 0
	v_mbcnt_hi_u32_b32 v1, -1, v1
	v_and_b32_e32 v2, 64, v1
	v_add_u32_e32 v2, 64, v2
	v_xor_b32_e32 v3, 32, v1
	v_cmp_lt_i32_e32 vcc, v3, v2
	v_or_b32_e32 v16, 0x400, v14
	v_or_b32_e32 v18, 0x500, v14
	v_cndmask_b32_e32 v3, v1, v3, vcc
	v_lshlrev_b32_e32 v24, 2, v3
	v_xor_b32_e32 v3, 16, v1
	v_cmp_lt_i32_e32 vcc, v3, v2
	v_or_b32_e32 v20, 0x600, v14
	v_or_b32_e32 v22, 0x700, v14
	v_cndmask_b32_e32 v3, v1, v3, vcc
	v_lshlrev_b32_e32 v25, 2, v3
	v_xor_b32_e32 v3, 8, v1
	v_cmp_lt_i32_e32 vcc, v3, v2
	s_mov_b64 s[0:1], 0
	v_mov_b32_e32 v30, 0x358637bd
	v_cndmask_b32_e32 v3, v1, v3, vcc
	v_lshlrev_b32_e32 v26, 2, v3
	v_xor_b32_e32 v3, 4, v1
	v_cmp_lt_i32_e32 vcc, v3, v2
	s_mov_b32 s98, 0x800000
	s_movk_i32 s99, 0x1fff
	v_cndmask_b32_e32 v3, v1, v3, vcc
	v_lshlrev_b32_e32 v27, 2, v3
	v_xor_b32_e32 v3, 2, v1
	v_cmp_lt_i32_e32 vcc, v3, v2
	s_nop 1
	v_cndmask_b32_e32 v3, v1, v3, vcc
	v_lshlrev_b32_e32 v28, 2, v3
	v_xor_b32_e32 v3, 1, v1
	v_cmp_lt_i32_e32 vcc, v3, v2
	v_lshlrev_b32_e32 v2, 2, v14
	s_nop 0
	v_cndmask_b32_e32 v1, v1, v3, vcc
	v_mov_b32_e32 v3, 0
	v_lshl_add_u64 v[4:5], s[62:63], 0, v[2:3]
	v_lshlrev_b32_e32 v2, 2, v16
	v_lshl_add_u64 v[6:7], s[62:63], 0, v[2:3]
	v_lshlrev_b32_e32 v2, 2, v18
	v_lshl_add_u64 v[8:9], s[62:63], 0, v[2:3]
	v_lshlrev_b32_e32 v2, 2, v20
	v_lshl_add_u64 v[10:11], s[62:63], 0, v[2:3]
	v_lshlrev_b32_e32 v2, 2, v22
	v_lshlrev_b32_e32 v29, 2, v1
	v_lshl_add_u64 v[12:13], s[62:63], 0, v[2:3]
	v_lshlrev_b32_e32 v2, 2, v14
	v_lshlrev_b32_e32 v14, 2, v16
	v_mov_b32_e32 v15, v3
	v_lshlrev_b32_e32 v16, 2, v18
	v_mov_b32_e32 v17, v3
	v_lshlrev_b32_e32 v18, 2, v20
	v_mov_b32_e32 v19, v3
	v_lshlrev_b32_e32 v20, 2, v22
	v_mov_b32_e32 v21, v3
.Lp8e_loop:
	v_ashrrev_i32_e32 v1, 31, v0
	v_lshlrev_b64 v[22:23], 13, v[0:1]
	v_lshl_add_u64 v[88:89], s[28:29], 0, v[22:23]
	v_lshl_add_u64 v[92:93], s[30:31], 0, v[22:23]
	v_lshl_add_u64 v[22:23], v[88:89], 0, v[2:3]
	v_lshl_add_u64 v[64:65], v[92:93], 0, v[2:3]
	v_lshl_add_u64 v[100:101], v[88:89], 0, v[14:15]
	v_lshl_add_u64 v[68:69], v[92:93], 0, v[14:15]
	v_lshl_add_u64 v[102:103], v[88:89], 0, v[16:17]
	v_lshl_add_u64 v[76:77], v[92:93], 0, v[16:17]
	v_lshl_add_u64 v[104:105], v[88:89], 0, v[18:19]
	v_lshl_add_u64 v[84:85], v[92:93], 0, v[18:19]
	global_load_dwordx4 v[32:35], v[22:23], off
	global_load_dwordx4 v[36:39], v[22:23], off offset:1024
	global_load_dwordx4 v[40:43], v[64:65], off
	global_load_dwordx4 v[44:47], v[64:65], off offset:1024
	global_load_dwordx4 v[48:51], v[22:23], off offset:2048
	global_load_dwordx4 v[52:55], v[22:23], off offset:3072
	global_load_dwordx4 v[56:59], v[64:65], off offset:2048
	global_load_dwordx4 v[60:63], v[64:65], off offset:3072
	global_load_dwordx4 v[72:75], v[102:103], off
	global_load_dwordx4 v[80:83], v[104:105], off
	v_lshl_add_u64 v[106:107], v[88:89], 0, v[20:21]
	global_load_dwordx4 v[64:67], v[100:101], off
	global_load_dwordx4 v[88:91], v[106:107], off
	v_lshl_add_u64 v[108:109], v[92:93], 0, v[20:21]
	global_load_dwordx4 v[68:71], v[68:69], off
	v_add_u32_e32 v0, 0x600, v0
	global_load_dwordx4 v[76:79], v[76:77], off
	s_waitcnt vmcnt(11)
	v_pk_add_f32 v[32:33], v[32:33], v[40:41]
	global_load_dwordx4 v[84:87], v[84:85], off
	s_nop 0
	global_load_dwordx4 v[92:95], v[108:109], off
	global_load_dwordx4 v[96:99], v[4:5], off
	s_waitcnt vmcnt(13)
	v_pk_add_f32 v[36:37], v[36:37], v[44:45]
	v_pk_add_f32 v[34:35], v[34:35], v[42:43]
	s_waitcnt vmcnt(10)
	v_pk_add_f32 v[42:43], v[48:49], v[56:57]
	v_mul_f32_e32 v1, v33, v33
	v_mul_f32_e32 v31, v37, v37
	v_pk_add_f32 v[38:39], v[38:39], v[46:47]
	v_pk_add_f32 v[40:41], v[50:51], v[58:59]
	s_waitcnt vmcnt(9)
	v_pk_add_f32 v[44:45], v[54:55], v[62:63]
	v_pk_add_f32 v[46:47], v[52:53], v[60:61]
	s_waitcnt vmcnt(4)
	v_pk_add_f32 v[50:51], v[64:65], v[68:69]
	v_fmac_f32_e32 v1, v32, v32
	s_waitcnt vmcnt(3)
	v_pk_add_f32 v[54:55], v[72:73], v[76:77]
	v_fmac_f32_e32 v31, v36, v36
	v_pk_add_f32 v[48:49], v[66:67], v[70:71]
	v_mov_b32_e32 v66, v51
	v_mov_b32_e32 v67, v55
	v_fmac_f32_e32 v1, v34, v34
	v_fmac_f32_e32 v31, v38, v38
	v_pk_add_f32 v[52:53], v[74:75], v[78:79]
	v_mov_b32_e32 v64, v50
	v_mov_b32_e32 v65, v54
	v_pk_mul_f32 v[66:67], v[66:67], v[66:67]
	v_fmac_f32_e32 v1, v35, v35
	v_fmac_f32_e32 v31, v39, v39
	v_mov_b32_e32 v68, v48
	v_mov_b32_e32 v69, v52
	v_pk_fma_f32 v[64:65], v[64:65], v[64:65], v[66:67]
	v_add_f32_e32 v1, v1, v31
	v_mov_b32_e32 v70, v49
	v_mov_b32_e32 v71, v53
	v_pk_fma_f32 v[64:65], v[68:69], v[68:69], v[64:65]
	s_waitcnt vmcnt(2)
	v_pk_add_f32 v[58:59], v[80:81], v[84:85]
	v_mul_f32_e32 v80, v43, v43
	v_mul_f32_e32 v81, v47, v47
	v_fmac_f32_e32 v80, v42, v42
	s_waitcnt vmcnt(1)
	v_pk_add_f32 v[62:63], v[88:89], v[92:93]
	v_fmac_f32_e32 v81, v46, v46
	v_fmac_f32_e32 v80, v40, v40
	v_mov_b32_e32 v74, v59
	v_mov_b32_e32 v75, v63
	v_fmac_f32_e32 v81, v44, v44
	v_fmac_f32_e32 v80, v41, v41
	v_pk_add_f32 v[56:57], v[82:83], v[86:87]
	v_pk_add_f32 v[60:61], v[90:91], v[94:95]
	v_mov_b32_e32 v72, v58
	v_mov_b32_e32 v73, v62
	v_pk_mul_f32 v[74:75], v[74:75], v[74:75]
	v_fmac_f32_e32 v81, v45, v45
	v_add_f32_e32 v1, v1, v80
	v_mov_b32_e32 v76, v56
	v_mov_b32_e32 v77, v60
	v_pk_fma_f32 v[66:67], v[72:73], v[72:73], v[74:75]
	v_pk_fma_f32 v[64:65], v[70:71], v[70:71], v[64:65]
	v_add_f32_e32 v1, v1, v81
	v_mov_b32_e32 v78, v57
	v_mov_b32_e32 v79, v61
	v_pk_fma_f32 v[66:67], v[76:77], v[76:77], v[66:67]
	v_add_f32_e32 v1, v1, v64
	v_pk_fma_f32 v[66:67], v[78:79], v[78:79], v[66:67]
	v_add_f32_e32 v1, v1, v65
	v_add_f32_e32 v1, v1, v66
	v_add_f32_e32 v1, v1, v67
	ds_bpermute_b32 v31, v24, v1
	s_waitcnt lgkmcnt(0)
	v_add_f32_e32 v1, v1, v31
	ds_bpermute_b32 v31, v25, v1
	s_waitcnt lgkmcnt(0)
	v_add_f32_e32 v1, v1, v31
	ds_bpermute_b32 v31, v26, v1
	s_waitcnt lgkmcnt(0)
	v_add_f32_e32 v1, v1, v31
	ds_bpermute_b32 v31, v27, v1
	s_waitcnt lgkmcnt(0)
	v_add_f32_e32 v1, v1, v31
	ds_bpermute_b32 v31, v28, v1
	s_waitcnt lgkmcnt(0)
	v_add_f32_e32 v1, v1, v31
	ds_bpermute_b32 v31, v29, v1
	s_waitcnt lgkmcnt(0)
	v_add_f32_e32 v1, v1, v31
	v_fmamk_f32 v1, v1, 0x3a000000, v30
	v_mul_f32_e32 v31, 0x4b800000, v1
	v_cmp_gt_f32_e32 vcc, s98, v1
	s_nop 1
	v_cndmask_b32_e32 v1, v1, v31, vcc
	v_rsq_f32_e32 v1, v1
	s_nop 0
	v_mul_f32_e32 v31, 0x45800000, v1
	v_cndmask_b32_e32 v64, v1, v31, vcc
	v_pk_mul_f32 v[32:33], v[32:33], v[64:65] op_sel_hi:[1,0]
	v_pk_mul_f32 v[34:35], v[34:35], v[64:65] op_sel_hi:[1,0]
	s_waitcnt vmcnt(0)
	v_pk_mul_f32 v[32:33], v[96:97], v[32:33]
	v_pk_mul_f32 v[34:35], v[98:99], v[34:35]
	global_store_dwordx4 v[22:23], v[32:35], off nt
	global_load_dwordx4 v[32:35], v[4:5], off offset:1024
	v_pk_mul_f32 v[38:39], v[38:39], v[64:65] op_sel_hi:[1,0]
	v_pk_mul_f32 v[36:37], v[36:37], v[64:65] op_sel_hi:[1,0]
	v_cmp_lt_i32_e32 vcc, s99, v0
	s_or_b64 s[0:1], vcc, s[0:1]
	s_waitcnt vmcnt(0)
	v_pk_mul_f32 v[32:33], v[32:33], v[36:37]
	v_pk_mul_f32 v[34:35], v[34:35], v[38:39]
	global_store_dwordx4 v[22:23], v[32:35], off offset:1024 nt
	global_load_dwordx4 v[32:35], v[4:5], off offset:2048
	v_pk_mul_f32 v[36:37], v[40:41], v[64:65] op_sel_hi:[1,0]
	v_pk_mul_f32 v[38:39], v[42:43], v[64:65] op_sel_hi:[1,0]
	s_waitcnt vmcnt(0)
	v_pk_mul_f32 v[34:35], v[34:35], v[36:37]
	v_pk_mul_f32 v[32:33], v[32:33], v[38:39]
	global_store_dwordx4 v[22:23], v[32:35], off offset:2048 nt
	global_load_dwordx4 v[32:35], v[4:5], off offset:3072
	v_pk_mul_f32 v[36:37], v[44:45], v[64:65] op_sel_hi:[1,0]
	v_pk_mul_f32 v[38:39], v[46:47], v[64:65] op_sel_hi:[1,0]
	s_waitcnt vmcnt(0)
	v_pk_mul_f32 v[34:35], v[34:35], v[36:37]
	v_pk_mul_f32 v[32:33], v[32:33], v[38:39]
	global_store_dwordx4 v[22:23], v[32:35], off offset:3072 nt
	global_load_dwordx4 v[32:35], v[6:7], off
	v_pk_mul_f32 v[22:23], v[48:49], v[64:65] op_sel_hi:[1,0]
	v_pk_mul_f32 v[36:37], v[50:51], v[64:65] op_sel_hi:[1,0]
	s_waitcnt vmcnt(0)
	v_pk_mul_f32 v[34:35], v[34:35], v[22:23]
	v_pk_mul_f32 v[32:33], v[32:33], v[36:37]
	global_store_dwordx4 v[100:101], v[32:35], off nt
	global_load_dwordx4 v[32:35], v[8:9], off
	v_pk_mul_f32 v[22:23], v[52:53], v[64:65] op_sel_hi:[1,0]
	v_pk_mul_f32 v[36:37], v[54:55], v[64:65] op_sel_hi:[1,0]
	s_waitcnt vmcnt(0)
	v_pk_mul_f32 v[34:35], v[34:35], v[22:23]
	v_pk_mul_f32 v[32:33], v[32:33], v[36:37]
	global_store_dwordx4 v[102:103], v[32:35], off nt
	global_load_dwordx4 v[32:35], v[10:11], off
	v_pk_mul_f32 v[22:23], v[56:57], v[64:65] op_sel_hi:[1,0]
	v_pk_mul_f32 v[36:37], v[58:59], v[64:65] op_sel_hi:[1,0]
	s_waitcnt vmcnt(0)
	v_pk_mul_f32 v[34:35], v[34:35], v[22:23]
	v_pk_mul_f32 v[32:33], v[32:33], v[36:37]
	global_store_dwordx4 v[104:105], v[32:35], off nt
	global_load_dwordx4 v[32:35], v[12:13], off
	v_pk_mul_f32 v[22:23], v[60:61], v[64:65] op_sel_hi:[1,0]
	v_pk_mul_f32 v[36:37], v[62:63], v[64:65] op_sel_hi:[1,0]
	s_waitcnt vmcnt(0)
	v_pk_mul_f32 v[34:35], v[22:23], v[34:35]
	v_pk_mul_f32 v[32:33], v[36:37], v[32:33]
	global_store_dwordx4 v[106:107], v[32:35], off nt
	s_andn2_b64 exec, exec, s[0:1]
	s_cbranch_execnz .Lp8e_loop
.Lp8e_end:
	s_mov_b64 exec, -1
.Lp8e_skip:
.LBB0_1089:
	s_waitcnt vmcnt(0)
	s_waitcnt vmcnt(0) lgkmcnt(0)
	s_barrier
	s_mov_b64 s[0:1], exec
	v_readlane_b32 s4, v239, 4
	v_readlane_b32 s5, v239, 5
	s_and_b64 s[4:5], s[0:1], s[4:5]
	s_mov_b64 exec, s[4:5]
	s_cbranch_execz .LBB0_1137
	s_add_i32 s3, 0, 0x21ff0
	v_mov_b32_e32 v0, s3
	s_waitcnt vmcnt(0) expcnt(0) lgkmcnt(0)
	ds_read_b32 v2, v0
	s_add_i32 s3, 0, 0x21ff4
	v_mov_b32_e32 v0, s3
	ds_read_b32 v0, v0
	s_waitcnt lgkmcnt(1)
	v_cmp_ne_u32_e32 vcc, 0, v2
	s_cbranch_vccnz .LBB0_1105
	s_mov_b32 s3, 1
	v_mov_b32_e32 v16, 0
	s_branch .LBB0_1093

.LBB0_1137:
	s_or_b64 exec, exec, s[0:1]
	s_waitcnt lgkmcnt(0)
	s_barrier
	s_movk_i32 s0, 0x2400
	v_ashrrev_i32_e32 v0, 6, v176
	v_lshl_add_u32 v0, s2, 3, v0
	v_add_u32_e32 v0, s100, v0
	v_cmp_gt_i32_e32 vcc, s0, v0
	s_and_saveexec_b64 s[0:1], vcc
	s_cbranch_execz .LBB0_1140
	v_lshlrev_b32_e32 v1, 2, v176
	v_and_b32_e32 v14, 0xfc, v1
	v_mbcnt_lo_u32_b32 v1, -1, 0
	v_mbcnt_hi_u32_b32 v1, -1, v1
	v_and_b32_e32 v2, 64, v1
	v_add_u32_e32 v2, 64, v2
	v_xor_b32_e32 v3, 32, v1
	v_cmp_lt_i32_e32 vcc, v3, v2
	v_or_b32_e32 v16, 0x400, v14
	v_or_b32_e32 v18, 0x500, v14
	v_cndmask_b32_e32 v3, v1, v3, vcc
	v_lshlrev_b32_e32 v24, 2, v3
	v_xor_b32_e32 v3, 16, v1
	v_cmp_lt_i32_e32 vcc, v3, v2
	v_or_b32_e32 v20, 0x600, v14
	v_or_b32_e32 v22, 0x700, v14
	v_cndmask_b32_e32 v3, v1, v3, vcc
	v_lshlrev_b32_e32 v25, 2, v3
	v_xor_b32_e32 v3, 8, v1
	v_cmp_lt_i32_e32 vcc, v3, v2
	s_mov_b64 s[0:1], 0
	v_mov_b32_e32 v30, 0x358637bd
	v_cndmask_b32_e32 v3, v1, v3, vcc
	v_lshlrev_b32_e32 v26, 2, v3
	v_xor_b32_e32 v3, 4, v1
	v_cmp_lt_i32_e32 vcc, v3, v2
	s_mov_b32 s2, 0x800000
	s_movk_i32 s3, 0x23ff
	v_cndmask_b32_e32 v3, v1, v3, vcc
	v_lshlrev_b32_e32 v27, 2, v3
	v_xor_b32_e32 v3, 2, v1
	v_cmp_lt_i32_e32 vcc, v3, v2
	s_nop 1
	v_cndmask_b32_e32 v3, v1, v3, vcc
	v_lshlrev_b32_e32 v28, 2, v3
	v_xor_b32_e32 v3, 1, v1
	v_cmp_lt_i32_e32 vcc, v3, v2
	v_lshlrev_b32_e32 v2, 2, v14
	s_nop 0
	v_cndmask_b32_e32 v1, v1, v3, vcc
	v_mov_b32_e32 v3, 0
	v_lshl_add_u64 v[4:5], s[62:63], 0, v[2:3]
	v_lshlrev_b32_e32 v2, 2, v16
	v_lshl_add_u64 v[6:7], s[62:63], 0, v[2:3]
	v_lshlrev_b32_e32 v2, 2, v18
	v_lshl_add_u64 v[8:9], s[62:63], 0, v[2:3]
	v_lshlrev_b32_e32 v2, 2, v20
	v_lshl_add_u64 v[10:11], s[62:63], 0, v[2:3]
	v_lshlrev_b32_e32 v2, 2, v22
	v_lshlrev_b32_e32 v29, 2, v1
	v_lshl_add_u64 v[12:13], s[62:63], 0, v[2:3]
	v_lshlrev_b32_e32 v2, 2, v14
	v_lshlrev_b32_e32 v14, 2, v16
	v_mov_b32_e32 v15, v3
	v_lshlrev_b32_e32 v16, 2, v18
	v_mov_b32_e32 v17, v3
	v_lshlrev_b32_e32 v18, 2, v20
	v_mov_b32_e32 v19, v3
	v_lshlrev_b32_e32 v20, 2, v22
	v_mov_b32_e32 v21, v3
